# ev-out RESID epilogue pipelined as well (SQRELU + both out-proj RESID epilogues rewritten)
# baseline (speedup 1.0000x reference)
; template <int EPI>
; DI float epi8(const Epi& e, int r, int c, f32x4 v0, f32x4 v1, float rinv, float4 s0, float4 s1, float4 t0, float4 t1) {
;     ...
;   } else if constexpr (EPI == EPI_RESID) {
;     const float* src; float* dst;
;     if (r < NX) { src = e.xi + (size_t)r * 1024 + c; dst = e.xo + (size_t)r * 1024 + c; }
;     else { int rc = r - NX; src = e.ci + (size_t)rc * 1024 + c; dst = e.co + (size_t)rc * 1024 + c; }
;     float4 x0 = *(const float4*)src, x1 = *(const float4*)(src + 4);
;     float4 o0, o1;
;     o0.x = x0.x + s0.x * v0[0]; o0.y = x0.y + s0.y * v0[1]; o0.z = x0.z + s0.z * v0[2]; o0.w = x0.w + s0.w * v0[3];
;     o1.x = x1.x + s1.x * v1[0]; o1.y = x1.y + s1.y * v1[1]; o1.z = x1.z + s1.z * v1[2]; o1.w = x1.w + s1.w * v1[3];
;     *(float4*)dst = o0; *(float4*)(dst + 4) = o1;
;     if (e.hout) {
;       uint4 h;
;       h.x = pack2(o0.x * t0.x, o0.y * t0.y); h.y = pack2(o0.z * t0.z, o0.w * t0.w);
;       h.z = pack2(o1.x * t1.x, o1.y * t1.y); h.w = pack2(o1.z * t1.z, o1.w * t1.w);
;       *(uint4*)(e.hout + (size_t)r * 1024 + c) = h;
;       return (o0.x * o0.x + o0.y * o0.y) + (o0.z * o0.z + o0.w * o0.w) + (o1.x * o1.x + o1.y * o1.y) + (o1.z * o1.z + o1.w * o1.w);
;     }
; template <int EPI>
; DI void gemm_phase(const u16* __restrict__ A, int lda, const u16* __restrict__ Bt, int ldb,
;                    int M, int N, int K, const Epi& e, unsigned char* shmraw, int wv, int slot) {
;     ...
;         const int c = bcol + bj * HALF + wc2 * 32 + fq2 * 8;
;         cs[bj][0] = cs[bj][1] = ct[bj][0] = ct[bj][1] = make_float4(0.f, 0.f, 0.f, 0.f);
;         if constexpr (EPI == EPI_FT || EPI == EPI_VT) {
;           if (e.stats) { f32x4 ra = row_rinv4(e.stats, c), rb = row_rinv4(e.stats, c + 4); cs[bj][0] = make_float4(ra[0], ra[1], ra[2], ra[3]); cs[bj][1] = make_float4(rb[0], rb[1], rb[2], rb[3]); }
;         } else if constexpr (EPI == EPI_STORE || EPI == EPI_SQRELU) {
;           if (e.stats) { const float* sp = e.shw + (size_t)mrow_t * 4096 + c; cs[bj][0] = *(const float4*)sp; cs[bj][1] = *(const float4*)(sp + 4); }
;         } else if constexpr (EPI == EPI_RESID) {
;           const float* gp = e.gate + (size_t)mrow_t * 6144 + c; cs[bj][0] = *(const float4*)gp; cs[bj][1] = *(const float4*)(gp + 4);
;           if (e.hout) {
;             const float* np = e.ngain + c; const float* scp = e.nscale + (size_t)mrow_t * 6144 + c;
.LBB0_1017:
	v_mbcnt_lo_u32_b32 v210, -1, 0
	v_mbcnt_hi_u32_b32 v210, -1, v210
	v_readlane_b32 s14, v255, 36
	v_readlane_b32 s15, v255, 35
	v_readlane_b32 s36, v255, 38
	v_readlane_b32 s37, v255, 37
	s_sub_u32 s36, s36, 0x10000000
	s_subb_u32 s37, s37, 0
	s_cmp_lt_i32 s12, 0x10000
	s_cselect_b32 s14, s14, s36
	s_cselect_b32 s15, s15, s37
	v_readlane_b32 s22, v255, 23
	v_readlane_b32 s23, v255, 24
	s_mov_b32 s36, s87
	s_mov_b32 s37, s16
	s_sub_u32 s36, s36, 0x10000000
	s_subb_u32 s37, s37, 0
	s_cmp_lt_i32 s12, 0x10000
	s_cselect_b32 s22, s22, s36
	s_cselect_b32 s23, s23, s37
	s_mov_b32 s10, s82
	s_mov_b32 s11, s83
	v_add_u32_e32 v154, s53, v210
	v_bfe_u32 v211, v154, 6, 2
	v_lshrrev_b32_e32 v0, 1, v210
	s_lshl_b32 s1, s31, 8
	v_lshlrev_b32_e32 v218, 5, v211
	v_and_b32_e32 v0, 24, v0
	v_or3_b32 v218, v218, v0, s1
	v_and_b32_e32 v155, 15, v210
	v_ashrrev_i32_e32 v209, 8, v154
	v_or_b32_e32 v0, s12, v155
	v_lshl_add_u32 v0, v209, 6, v0
	v_lshlrev_b32_e32 v216, 12, v0
	v_lshl_add_u32 v216, v218, 2, v216
	v_lshlrev_b32_e32 v218, 2, v218
	v_lshrrev_b32_e32 v217, 1, v216
	s_min_i32 s19, s43, 0x100
	s_ashr_i32 s19, s19, 3
	s_mul_i32 s19, s19, 0x6000
	s_add_u32 s36, s25, s19
	s_addc_u32 s37, s26, 0
	global_load_dwordx4 v[30:33], v218, s[36:37]
	global_load_dwordx4 v[26:29], v218, s[36:37] offset:16
	global_load_dwordx4 v[22:25], v218, s[36:37] offset:512
	global_load_dwordx4 v[18:21], v218, s[36:37] offset:528
	global_load_dwordx4 v[156:159], v218, s[6:7]
	global_load_dwordx4 v[160:163], v218, s[6:7] offset:16
	global_load_dwordx4 v[164:167], v218, s[6:7] offset:512
	global_load_dwordx4 v[168:171], v218, s[6:7] offset:528
	s_add_u32 s36, s27, s19
	s_addc_u32 s37, s28, 0
	global_load_dwordx4 v[242:245], v218, s[36:37]
	global_load_dwordx4 v[246:249], v218, s[36:37] offset:16
	global_load_dwordx4 v[220:223], v218, s[36:37] offset:512
	global_load_dwordx4 v[224:227], v218, s[36:37] offset:528
	global_load_dwordx4 v[172:175], v216, s[14:15]
	global_load_dwordx4 v[176:179], v216, s[14:15] offset:16
	global_load_dwordx4 v[180:183], v216, s[14:15] offset:512
	global_load_dwordx4 v[184:187], v216, s[14:15] offset:528
	s_add_u32 s14, s14, 0x10000
	s_addc_u32 s15, s15, 0
	global_load_dwordx4 v[188:191], v216, s[14:15]
	global_load_dwordx4 v[230:233], v216, s[14:15] offset:16
	global_load_dwordx4 v[234:237], v216, s[14:15] offset:512
	global_load_dwordx4 v[238:241], v216, s[14:15] offset:528
	s_add_u32 s14, s14, 0x10000
	s_addc_u32 s15, s15, 0
	s_waitcnt vmcnt(8)
	v_pk_add_f32 v[242:243], v[242:243], 1.0 op_sel_hi:[1,0]
	v_pk_add_f32 v[244:245], v[244:245], 1.0 op_sel_hi:[1,0]
	v_pk_add_f32 v[246:247], v[246:247], 1.0 op_sel_hi:[1,0]
	v_pk_add_f32 v[248:249], v[248:249], 1.0 op_sel_hi:[1,0]
	v_pk_add_f32 v[220:221], v[220:221], 1.0 op_sel_hi:[1,0]
	v_pk_add_f32 v[222:223], v[222:223], 1.0 op_sel_hi:[1,0]
	v_pk_add_f32 v[224:225], v[224:225], 1.0 op_sel_hi:[1,0]
	v_pk_add_f32 v[226:227], v[226:227], 1.0 op_sel_hi:[1,0]
	v_pk_mul_f32 v[156:157], v[156:157], v[242:243]
	v_pk_mul_f32 v[158:159], v[158:159], v[244:245]
	v_pk_mul_f32 v[160:161], v[160:161], v[246:247]
	v_pk_mul_f32 v[162:163], v[162:163], v[248:249]
	v_pk_mul_f32 v[164:165], v[164:165], v[220:221]
	v_pk_mul_f32 v[166:167], v[166:167], v[222:223]
	v_pk_mul_f32 v[168:169], v[168:169], v[224:225]
	v_pk_mul_f32 v[170:171], v[170:171], v[226:227]
	global_load_dwordx4 v[242:245], v216, s[14:15]
	global_load_dwordx4 v[246:249], v216, s[14:15] offset:16
	global_load_dwordx4 v[220:223], v216, s[14:15] offset:512
	global_load_dwordx4 v[224:227], v216, s[14:15] offset:528
	s_add_u32 s14, s14, 0x10000
	s_addc_u32 s15, s15, 0
	s_waitcnt vmcnt(8)
	v_pk_fma_f32 v[138:139], v[138:139], v[30:31], v[172:173]
	v_pk_fma_f32 v[140:141], v[140:141], v[32:33], v[174:175]
	v_pk_fma_f32 v[146:147], v[146:147], v[26:27], v[176:177]
	v_pk_fma_f32 v[148:149], v[148:149], v[28:29], v[178:179]
	v_pk_fma_f32 v[54:55], v[54:55], v[22:23], v[180:181]
	v_pk_fma_f32 v[56:57], v[56:57], v[24:25], v[182:183]
	v_pk_fma_f32 v[134:135], v[134:135], v[18:19], v[184:185]
	v_pk_fma_f32 v[136:137], v[136:137], v[20:21], v[186:187]
	global_store_dwordx4 v216, v[138:141], s[22:23]
	global_store_dwordx4 v216, v[146:149], s[22:23] offset:16
	v_pk_mul_f32 v[142:143], v[156:157], v[138:139]
	v_pk_mul_f32 v[144:145], v[158:159], v[140:141]
	v_pk_mul_f32 v[172:173], v[160:161], v[146:147]
	v_pk_mul_f32 v[174:175], v[162:163], v[148:149]
	v_cvt_pk_bf16_f32 v142, v142, v143
	v_cvt_pk_bf16_f32 v143, v144, v145
	v_cvt_pk_bf16_f32 v144, v172, v173
	v_cvt_pk_bf16_f32 v145, v174, v175
	global_store_dwordx4 v217, v[142:145], s[10:11]
	global_store_dwordx4 v216, v[54:57], s[22:23] offset:512
	global_store_dwordx4 v216, v[134:137], s[22:23] offset:528
	v_pk_mul_f32 v[212:213], v[164:165], v[54:55]
	v_pk_mul_f32 v[214:215], v[166:167], v[56:57]
	v_pk_mul_f32 v[172:173], v[168:169], v[134:135]
	v_pk_mul_f32 v[174:175], v[170:171], v[136:137]
	v_cvt_pk_bf16_f32 v212, v212, v213
	v_cvt_pk_bf16_f32 v213, v214, v215
	v_cvt_pk_bf16_f32 v214, v172, v173
	v_cvt_pk_bf16_f32 v215, v174, v175
	global_store_dwordx4 v217, v[212:215], s[10:11] offset:256
	v_pk_mul_f32 v[228:229], v[138:139], v[138:139]
	v_pk_fma_f32 v[228:229], v[140:141], v[140:141], v[228:229]
	v_pk_fma_f32 v[228:229], v[146:147], v[146:147], v[228:229]
	v_pk_fma_f32 v[228:229], v[148:149], v[148:149], v[228:229]
	v_pk_fma_f32 v[228:229], v[54:55], v[54:55], v[228:229]
	v_pk_fma_f32 v[228:229], v[56:57], v[56:57], v[228:229]
	v_pk_fma_f32 v[228:229], v[134:135], v[134:135], v[228:229]
	v_pk_fma_f32 v[228:229], v[136:137], v[136:137], v[228:229]
	global_load_dwordx4 v[172:175], v216, s[14:15]
	global_load_dwordx4 v[176:179], v216, s[14:15] offset:16
	global_load_dwordx4 v[180:183], v216, s[14:15] offset:512
	global_load_dwordx4 v[184:187], v216, s[14:15] offset:528
	s_add_u32 s14, s14, 0x50000
	s_addc_u32 s15, s15, 0
	v_add_f32_e32 v138, v228, v229
	s_add_u32 s22, s22, 0x10000
	s_addc_u32 s23, s23, 0
	s_add_u32 s10, s10, 0x8000
	s_addc_u32 s11, s11, 0
	s_waitcnt vmcnt(14)
; template <int EPI>
; DI float epi8(const Epi& e, int r, int c, f32x4 v0, f32x4 v1, float rinv, float4 s0, float4 s1, float4 t0, float4 t1) {
;     ...
;   } else if constexpr (EPI == EPI_RESID) {
;     const float* src; float* dst;
;     if (r < NX) { src = e.xi + (size_t)r * 1024 + c; dst = e.xo + (size_t)r * 1024 + c; }
;     else { int rc = r - NX; src = e.ci + (size_t)rc * 1024 + c; dst = e.co + (size_t)rc * 1024 + c; }
;     float4 x0 = *(const float4*)src, x1 = *(const float4*)(src + 4);
;     float4 o0, o1;
;     o0.x = x0.x + s0.x * v0[0]; o0.y = x0.y + s0.y * v0[1]; o0.z = x0.z + s0.z * v0[2]; o0.w = x0.w + s0.w * v0[3];
;     o1.x = x1.x + s1.x * v1[0]; o1.y = x1.y + s1.y * v1[1]; o1.z = x1.z + s1.z * v1[2]; o1.w = x1.w + s1.w * v1[3];
;     *(float4*)dst = o0; *(float4*)(dst + 4) = o1;
;     if (e.hout) {
;       uint4 h;
;       h.x = pack2(o0.x * t0.x, o0.y * t0.y); h.y = pack2(o0.z * t0.z, o0.w * t0.w);
;       h.z = pack2(o1.x * t1.x, o1.y * t1.y); h.w = pack2(o1.z * t1.z, o1.w * t1.w);
;       *(uint4*)(e.hout + (size_t)r * 1024 + c) = h;
;       return (o0.x * o0.x + o0.y * o0.y) + (o0.z * o0.z + o0.w * o0.w) + (o1.x * o1.x + o1.y * o1.y) + (o1.z * o1.z + o1.w * o1.w);
;     }
; template <int EPI>
; DI void gemm_phase(const u16* __restrict__ A, int lda, const u16* __restrict__ Bt, int ldb,
;                    int M, int N, int K, const Epi& e, unsigned char* shmraw, int wv, int slot) {
;     ...
;       float rowss[2][4];
; #pragma unroll
;       for (int ai = 0; ai < 2; ++ai)
; #pragma unroll
;         for (int m = 0; m < 4; ++m) {
;           const int row = brow + ai * HALF + wr2 * 64 + m * 16 + fr2;
;           float rinv = 1.f;
;           if constexpr (EPI == EPI_STORE || EPI == EPI_SQRELU) { if (e.stats) rinv = row_rinv(e.stats, row); }
;           if constexpr (EPI == EPI_FT || EPI == EPI_VT) { rinv = e.stats ? e.shw[(size_t)mrow_t * 4096 + row] : 0.f; }
;           float ss = 0.f;
; #pragma unroll
;           for (int bj = 0; bj < 2; ++bj)
;             ss += epi8<EPI>(e, row, bcol + bj * HALF + wc2 * 32 + fq2 * 8, acc[ai][bj][m][0], acc[ai][bj][m][1], rinv, cs[bj][0], cs[bj][1], ct[bj][0], ct[bj][1]);
;           rowss[ai][m] = ss;
;         }
	v_pk_fma_f32 v[54:55], v[50:51], v[30:31], v[188:189]
	v_pk_fma_f32 v[56:57], v[52:53], v[32:33], v[190:191]
	v_pk_fma_f32 v[50:51], v[70:71], v[26:27], v[230:231]
	v_pk_fma_f32 v[52:53], v[72:73], v[28:29], v[232:233]
	v_pk_fma_f32 v[70:71], v[66:67], v[22:23], v[234:235]
	v_pk_fma_f32 v[72:73], v[68:69], v[24:25], v[236:237]
	v_pk_fma_f32 v[66:67], v[86:87], v[18:19], v[238:239]
	v_pk_fma_f32 v[68:69], v[88:89], v[20:21], v[240:241]
	global_store_dwordx4 v216, v[54:57], s[22:23]
	global_store_dwordx4 v216, v[50:53], s[22:23] offset:16
	v_pk_mul_f32 v[142:143], v[156:157], v[54:55]
	v_pk_mul_f32 v[144:145], v[158:159], v[56:57]
	v_pk_mul_f32 v[188:189], v[160:161], v[50:51]
	v_pk_mul_f32 v[190:191], v[162:163], v[52:53]
	v_cvt_pk_bf16_f32 v142, v142, v143
	v_cvt_pk_bf16_f32 v143, v144, v145
	v_cvt_pk_bf16_f32 v144, v188, v189
	v_cvt_pk_bf16_f32 v145, v190, v191
	global_store_dwordx4 v217, v[142:145], s[10:11]
	global_store_dwordx4 v216, v[70:73], s[22:23] offset:512
	global_store_dwordx4 v216, v[66:69], s[22:23] offset:528
	v_pk_mul_f32 v[212:213], v[164:165], v[70:71]
	v_pk_mul_f32 v[214:215], v[166:167], v[72:73]
	v_pk_mul_f32 v[188:189], v[168:169], v[66:67]
	v_pk_mul_f32 v[190:191], v[170:171], v[68:69]
	v_cvt_pk_bf16_f32 v212, v212, v213
	v_cvt_pk_bf16_f32 v213, v214, v215
	v_cvt_pk_bf16_f32 v214, v188, v189
	v_cvt_pk_bf16_f32 v215, v190, v191
	global_store_dwordx4 v217, v[212:215], s[10:11] offset:256
	global_load_dwordx4 v[188:191], v216, s[14:15]
	global_load_dwordx4 v[230:233], v216, s[14:15] offset:16
	global_load_dwordx4 v[234:237], v216, s[14:15] offset:512
	global_load_dwordx4 v[238:241], v216, s[14:15] offset:528
	s_add_u32 s14, s14, 0x10000
	s_addc_u32 s15, s15, 0
	s_add_u32 s22, s22, 0x10000
	s_addc_u32 s23, s23, 0
	s_add_u32 s10, s10, 0x8000
	s_addc_u32 s11, s11, 0
	s_waitcnt vmcnt(20)
	v_pk_fma_f32 v[86:87], v[82:83], v[30:31], v[242:243]
	v_pk_fma_f32 v[88:89], v[84:85], v[32:33], v[244:245]
	v_pk_fma_f32 v[82:83], v[102:103], v[26:27], v[246:247]
	v_pk_fma_f32 v[84:85], v[104:105], v[28:29], v[248:249]
	v_pk_fma_f32 v[102:103], v[98:99], v[22:23], v[220:221]
	v_pk_fma_f32 v[104:105], v[100:101], v[24:25], v[222:223]
	v_pk_fma_f32 v[98:99], v[118:119], v[18:19], v[224:225]
	v_pk_fma_f32 v[100:101], v[120:121], v[20:21], v[226:227]
	global_store_dwordx4 v216, v[86:89], s[22:23]
	global_store_dwordx4 v216, v[82:85], s[22:23] offset:16
	v_pk_mul_f32 v[142:143], v[156:157], v[86:87]
	v_pk_mul_f32 v[144:145], v[158:159], v[88:89]
	v_pk_mul_f32 v[242:243], v[160:161], v[82:83]
	v_pk_mul_f32 v[244:245], v[162:163], v[84:85]
	v_cvt_pk_bf16_f32 v142, v142, v143
	v_cvt_pk_bf16_f32 v143, v144, v145
	v_cvt_pk_bf16_f32 v144, v242, v243
	v_cvt_pk_bf16_f32 v145, v244, v245
	global_store_dwordx4 v217, v[142:145], s[10:11]
	global_store_dwordx4 v216, v[102:105], s[22:23] offset:512
	global_store_dwordx4 v216, v[98:101], s[22:23] offset:528
	v_pk_mul_f32 v[212:213], v[164:165], v[102:103]
	v_pk_mul_f32 v[214:215], v[166:167], v[104:105]
	v_pk_mul_f32 v[242:243], v[168:169], v[98:99]
	v_pk_mul_f32 v[244:245], v[170:171], v[100:101]
	v_cvt_pk_bf16_f32 v212, v212, v213
	v_cvt_pk_bf16_f32 v213, v214, v215
	v_cvt_pk_bf16_f32 v214, v242, v243
	v_cvt_pk_bf16_f32 v215, v244, v245
	global_store_dwordx4 v217, v[212:215], s[10:11] offset:256
	global_load_dwordx4 v[242:245], v216, s[14:15]
	global_load_dwordx4 v[246:249], v216, s[14:15] offset:16
	global_load_dwordx4 v[220:223], v216, s[14:15] offset:512
	global_load_dwordx4 v[224:227], v216, s[14:15] offset:528
	s_add_u32 s14, s14, 0x10000
	s_addc_u32 s15, s15, 0
	s_add_u32 s22, s22, 0x10000
	s_addc_u32 s23, s23, 0
	s_add_u32 s10, s10, 0x8000
	s_addc_u32 s11, s11, 0
	s_waitcnt vmcnt(20)
	v_pk_fma_f32 v[118:119], v[114:115], v[30:31], v[172:173]
	v_pk_fma_f32 v[120:121], v[116:117], v[32:33], v[174:175]
	v_pk_fma_f32 v[114:115], v[130:131], v[26:27], v[176:177]
	v_pk_fma_f32 v[116:117], v[132:133], v[28:29], v[178:179]
	v_pk_fma_f32 v[130:131], v[122:123], v[22:23], v[180:181]
	v_pk_fma_f32 v[132:133], v[124:125], v[24:25], v[182:183]
	v_pk_fma_f32 v[122:123], v[126:127], v[18:19], v[184:185]
	v_pk_fma_f32 v[124:125], v[128:129], v[20:21], v[186:187]
	global_store_dwordx4 v216, v[118:121], s[22:23]
	global_store_dwordx4 v216, v[114:117], s[22:23] offset:16
	v_pk_mul_f32 v[142:143], v[156:157], v[118:119]
	v_pk_mul_f32 v[144:145], v[158:159], v[120:121]
	v_pk_mul_f32 v[172:173], v[160:161], v[114:115]
	v_pk_mul_f32 v[174:175], v[162:163], v[116:117]
	v_cvt_pk_bf16_f32 v142, v142, v143
	v_cvt_pk_bf16_f32 v143, v144, v145
	v_cvt_pk_bf16_f32 v144, v172, v173
	v_cvt_pk_bf16_f32 v145, v174, v175
	global_store_dwordx4 v217, v[142:145], s[10:11]
	global_store_dwordx4 v216, v[130:133], s[22:23] offset:512
	global_store_dwordx4 v216, v[122:125], s[22:23] offset:528
	v_pk_mul_f32 v[212:213], v[164:165], v[130:131]
	v_pk_mul_f32 v[214:215], v[166:167], v[132:133]
	v_pk_mul_f32 v[172:173], v[168:169], v[122:123]
	v_pk_mul_f32 v[174:175], v[170:171], v[124:125]
	v_cvt_pk_bf16_f32 v212, v212, v213
	v_cvt_pk_bf16_f32 v213, v214, v215
	v_cvt_pk_bf16_f32 v214, v172, v173
	v_cvt_pk_bf16_f32 v215, v174, v175
	global_store_dwordx4 v217, v[212:215], s[10:11] offset:256
	global_load_dwordx4 v[172:175], v216, s[14:15]
	global_load_dwordx4 v[176:179], v216, s[14:15] offset:16
	global_load_dwordx4 v[180:183], v216, s[14:15] offset:512
	global_load_dwordx4 v[184:187], v216, s[14:15] offset:528
	s_add_u32 s14, s14, 0x10000
	s_addc_u32 s15, s15, 0
	s_add_u32 s22, s22, 0x50000
	s_addc_u32 s23, s23, 0
	s_add_u32 s10, s10, 0x28000
	s_addc_u32 s11, s11, 0
	s_waitcnt vmcnt(20)
; DI float shx(float v, int o, int lane) { return __int_as_float(__builtin_amdgcn_ds_bpermute((lane ^ o) << 2, __float_as_int(v))); }
; template <int EPI>
; DI float epi8(const Epi& e, int r, int c, f32x4 v0, f32x4 v1, float rinv, float4 s0, float4 s1, float4 t0, float4 t1) {
;     ...
;   } else if constexpr (EPI == EPI_RESID) {
;     const float* src; float* dst;
;     if (r < NX) { src = e.xi + (size_t)r * 1024 + c; dst = e.xo + (size_t)r * 1024 + c; }
;     else { int rc = r - NX; src = e.ci + (size_t)rc * 1024 + c; dst = e.co + (size_t)rc * 1024 + c; }
;     float4 x0 = *(const float4*)src, x1 = *(const float4*)(src + 4);
;     float4 o0, o1;
;     o0.x = x0.x + s0.x * v0[0]; o0.y = x0.y + s0.y * v0[1]; o0.z = x0.z + s0.z * v0[2]; o0.w = x0.w + s0.w * v0[3];
;     o1.x = x1.x + s1.x * v1[0]; o1.y = x1.y + s1.y * v1[1]; o1.z = x1.z + s1.z * v1[2]; o1.w = x1.w + s1.w * v1[3];
;     *(float4*)dst = o0; *(float4*)(dst + 4) = o1;
;     if (e.hout) {
;       uint4 h;
;       h.x = pack2(o0.x * t0.x, o0.y * t0.y); h.y = pack2(o0.z * t0.z, o0.w * t0.w);
;       h.z = pack2(o1.x * t1.x, o1.y * t1.y); h.w = pack2(o1.z * t1.z, o1.w * t1.w);
;       *(uint4*)(e.hout + (size_t)r * 1024 + c) = h;
;       return (o0.x * o0.x + o0.y * o0.y) + (o0.z * o0.z + o0.w * o0.w) + (o1.x * o1.x + o1.y * o1.y) + (o1.z * o1.z + o1.w * o1.w);
;     }
; template <int EPI>
; DI void gemm_phase(const u16* __restrict__ A, int lda, const u16* __restrict__ Bt, int ldb,
;                    int M, int N, int K, const Epi& e, unsigned char* shmraw, int wv, int slot) {
;     ...
;       if constexpr (EPI == EPI_RESID) {
;         if (e.hout) {
;           float* red = (float*)SA(1, 1);
; #pragma unroll
;           for (int ai = 0; ai < 2; ++ai)
; #pragma unroll
;             for (int m = 0; m < 4; ++m) {
;               float v = rowss[ai][m];
;               v += shx(v, 16, lane2); v += shx(v, 32, lane2);
;               if (fq2 == 0) red[(ai * HALF + wr2 * 64 + m * 16 + fr2) * 4 + wc2] = v;
;             }
	v_pk_fma_f32 v[126:127], v[106:107], v[30:31], v[188:189]
	v_pk_fma_f32 v[128:129], v[108:109], v[32:33], v[190:191]
	v_pk_fma_f32 v[106:107], v[110:111], v[26:27], v[230:231]
	v_pk_fma_f32 v[108:109], v[112:113], v[28:29], v[232:233]
	v_pk_fma_f32 v[110:111], v[90:91], v[22:23], v[234:235]
	v_pk_fma_f32 v[112:113], v[92:93], v[24:25], v[236:237]
	v_pk_fma_f32 v[90:91], v[94:95], v[18:19], v[238:239]
	v_pk_fma_f32 v[92:93], v[96:97], v[20:21], v[240:241]
	global_store_dwordx4 v216, v[126:129], s[22:23]
	global_store_dwordx4 v216, v[106:109], s[22:23] offset:16
	v_pk_mul_f32 v[142:143], v[156:157], v[126:127]
	v_pk_mul_f32 v[144:145], v[158:159], v[128:129]
	v_pk_mul_f32 v[188:189], v[160:161], v[106:107]
	v_pk_mul_f32 v[190:191], v[162:163], v[108:109]
	v_cvt_pk_bf16_f32 v142, v142, v143
	v_cvt_pk_bf16_f32 v143, v144, v145
	v_cvt_pk_bf16_f32 v144, v188, v189
	v_cvt_pk_bf16_f32 v145, v190, v191
	global_store_dwordx4 v217, v[142:145], s[10:11]
	global_store_dwordx4 v216, v[110:113], s[22:23] offset:512
	global_store_dwordx4 v216, v[90:93], s[22:23] offset:528
	v_pk_mul_f32 v[212:213], v[164:165], v[110:111]
	v_pk_mul_f32 v[214:215], v[166:167], v[112:113]
	v_pk_mul_f32 v[188:189], v[168:169], v[90:91]
	v_pk_mul_f32 v[190:191], v[170:171], v[92:93]
	v_cvt_pk_bf16_f32 v212, v212, v213
	v_cvt_pk_bf16_f32 v213, v214, v215
	v_cvt_pk_bf16_f32 v214, v188, v189
	v_cvt_pk_bf16_f32 v215, v190, v191
	global_store_dwordx4 v217, v[212:215], s[10:11] offset:256
	global_load_dwordx4 v[188:191], v216, s[14:15]
	global_load_dwordx4 v[230:233], v216, s[14:15] offset:16
	global_load_dwordx4 v[234:237], v216, s[14:15] offset:512
	global_load_dwordx4 v[238:241], v216, s[14:15] offset:528
	s_add_u32 s22, s22, 0x10000
	s_addc_u32 s23, s23, 0
	s_add_u32 s10, s10, 0x8000
	s_addc_u32 s11, s11, 0
	s_waitcnt vmcnt(20)
	v_pk_fma_f32 v[94:95], v[74:75], v[30:31], v[242:243]
	v_pk_fma_f32 v[96:97], v[76:77], v[32:33], v[244:245]
	v_pk_fma_f32 v[74:75], v[78:79], v[26:27], v[246:247]
	v_pk_fma_f32 v[76:77], v[80:81], v[28:29], v[248:249]
	v_pk_fma_f32 v[78:79], v[58:59], v[22:23], v[220:221]
	v_pk_fma_f32 v[80:81], v[60:61], v[24:25], v[222:223]
	v_pk_fma_f32 v[58:59], v[62:63], v[18:19], v[224:225]
	v_pk_fma_f32 v[60:61], v[64:65], v[20:21], v[226:227]
	global_store_dwordx4 v216, v[94:97], s[22:23]
	global_store_dwordx4 v216, v[74:77], s[22:23] offset:16
	v_pk_mul_f32 v[142:143], v[156:157], v[94:95]
	v_pk_mul_f32 v[144:145], v[158:159], v[96:97]
	v_pk_mul_f32 v[242:243], v[160:161], v[74:75]
	v_pk_mul_f32 v[244:245], v[162:163], v[76:77]
	v_cvt_pk_bf16_f32 v142, v142, v143
	v_cvt_pk_bf16_f32 v143, v144, v145
	v_cvt_pk_bf16_f32 v144, v242, v243
	v_cvt_pk_bf16_f32 v145, v244, v245
	global_store_dwordx4 v217, v[142:145], s[10:11]
	global_store_dwordx4 v216, v[78:81], s[22:23] offset:512
	global_store_dwordx4 v216, v[58:61], s[22:23] offset:528
	v_pk_mul_f32 v[212:213], v[164:165], v[78:79]
	v_pk_mul_f32 v[214:215], v[166:167], v[80:81]
	v_pk_mul_f32 v[242:243], v[168:169], v[58:59]
	v_pk_mul_f32 v[244:245], v[170:171], v[60:61]
	v_cvt_pk_bf16_f32 v212, v212, v213
	v_cvt_pk_bf16_f32 v213, v214, v215
	v_cvt_pk_bf16_f32 v214, v242, v243
	v_cvt_pk_bf16_f32 v215, v244, v245
	global_store_dwordx4 v217, v[212:215], s[10:11] offset:256
	s_add_u32 s22, s22, 0x10000
	s_addc_u32 s23, s23, 0
	s_add_u32 s10, s10, 0x8000
	s_addc_u32 s11, s11, 0
	s_waitcnt vmcnt(16)
	v_pk_fma_f32 v[62:63], v[42:43], v[30:31], v[172:173]
	v_pk_fma_f32 v[64:65], v[44:45], v[32:33], v[174:175]
	v_pk_fma_f32 v[42:43], v[46:47], v[26:27], v[176:177]
	v_pk_fma_f32 v[44:45], v[48:49], v[28:29], v[178:179]
	v_pk_fma_f32 v[46:47], v[34:35], v[22:23], v[180:181]
	v_pk_fma_f32 v[48:49], v[36:37], v[24:25], v[182:183]
	v_pk_fma_f32 v[34:35], v[38:39], v[18:19], v[184:185]
	v_pk_fma_f32 v[36:37], v[40:41], v[20:21], v[186:187]
	global_store_dwordx4 v216, v[62:65], s[22:23]
	global_store_dwordx4 v216, v[42:45], s[22:23] offset:16
	v_pk_mul_f32 v[142:143], v[156:157], v[62:63]
	v_pk_mul_f32 v[144:145], v[158:159], v[64:65]
	v_pk_mul_f32 v[172:173], v[160:161], v[42:43]
	v_pk_mul_f32 v[174:175], v[162:163], v[44:45]
	v_cvt_pk_bf16_f32 v142, v142, v143
	v_cvt_pk_bf16_f32 v143, v144, v145
	v_cvt_pk_bf16_f32 v144, v172, v173
	v_cvt_pk_bf16_f32 v145, v174, v175
	global_store_dwordx4 v217, v[142:145], s[10:11]
	global_store_dwordx4 v216, v[46:49], s[22:23] offset:512
	global_store_dwordx4 v216, v[34:37], s[22:23] offset:528
	v_pk_mul_f32 v[212:213], v[164:165], v[46:47]
	v_pk_mul_f32 v[214:215], v[166:167], v[48:49]
	v_pk_mul_f32 v[172:173], v[168:169], v[34:35]
	v_pk_mul_f32 v[174:175], v[170:171], v[36:37]
	v_cvt_pk_bf16_f32 v212, v212, v213
	v_cvt_pk_bf16_f32 v213, v214, v215
	v_cvt_pk_bf16_f32 v214, v172, v173
	v_cvt_pk_bf16_f32 v215, v174, v175
	global_store_dwordx4 v217, v[212:215], s[10:11] offset:256
	s_add_u32 s22, s22, 0x10000
	s_addc_u32 s23, s23, 0
	s_add_u32 s10, s10, 0x8000
	s_addc_u32 s11, s11, 0
	s_waitcnt vmcnt(12)
	v_pk_fma_f32 v[30:31], v[10:11], v[30:31], v[188:189]
	v_pk_fma_f32 v[32:33], v[12:13], v[32:33], v[190:191]
	v_pk_fma_f32 v[10:11], v[14:15], v[26:27], v[230:231]
	v_pk_fma_f32 v[12:13], v[16:17], v[28:29], v[232:233]
	v_pk_fma_f32 v[14:15], v[2:3], v[22:23], v[234:235]
	v_pk_fma_f32 v[16:17], v[4:5], v[24:25], v[236:237]
	v_pk_fma_f32 v[2:3], v[6:7], v[18:19], v[238:239]
	v_pk_fma_f32 v[4:5], v[8:9], v[20:21], v[240:241]
	global_store_dwordx4 v216, v[30:33], s[22:23]
	global_store_dwordx4 v216, v[10:13], s[22:23] offset:16
	v_pk_mul_f32 v[142:143], v[156:157], v[30:31]
	v_pk_mul_f32 v[144:145], v[158:159], v[32:33]
	v_pk_mul_f32 v[188:189], v[160:161], v[10:11]
	v_pk_mul_f32 v[190:191], v[162:163], v[12:13]
	v_cvt_pk_bf16_f32 v142, v142, v143
	v_cvt_pk_bf16_f32 v143, v144, v145
	v_cvt_pk_bf16_f32 v144, v188, v189
	v_cvt_pk_bf16_f32 v145, v190, v191
	global_store_dwordx4 v217, v[142:145], s[10:11]
	global_store_dwordx4 v216, v[14:17], s[22:23] offset:512
	global_store_dwordx4 v216, v[2:5], s[22:23] offset:528
	v_pk_mul_f32 v[212:213], v[164:165], v[14:15]
	v_pk_mul_f32 v[214:215], v[166:167], v[16:17]
	v_pk_mul_f32 v[188:189], v[168:169], v[2:3]
	v_pk_mul_f32 v[190:191], v[170:171], v[4:5]
	v_cvt_pk_bf16_f32 v212, v212, v213
	v_cvt_pk_bf16_f32 v213, v214, v215
	v_cvt_pk_bf16_f32 v214, v188, v189
	v_cvt_pk_bf16_f32 v215, v190, v191
	global_store_dwordx4 v217, v[212:215], s[10:11] offset:256
	v_lshlrev_b32_e32 v0, 2, v210
	v_cmp_gt_u32_e32 vcc, 16, v210
	v_lshlrev_b32_e32 v18, 10, v209
	v_lshlrev_b32_e32 v19, 4, v155
	v_xor_b32_e32 v6, 64, v0
	ds_bpermute_b32 v8, v6, v138
	v_xor_b32_e32 v0, 0x80, v0
	v_lshl_add_u32 v7, v211, 2, 16
	v_add3_u32 v7, v7, v18, v19
	s_waitcnt lgkmcnt(0)
	v_add_f32_e32 v8, v138, v8
	ds_bpermute_b32 v9, v0, v8
	s_and_saveexec_b64 s[14:15], vcc
	s_cbranch_execz .LBB0_1019
	s_waitcnt lgkmcnt(0)
	v_add_f32_e32 v8, v8, v9
	ds_write_b32 v7, v8 offset:49152
